# on top: 964 dead SGPR-reload v_readlane removed from GEMM-phase unit loops/epilogues (global liveness; one s_nop 1 per removed run)
# speedup vs baseline: 1.0077x; 1.0048x over previous
.LBB0_65:
	s_ashr_i32 s31, s30, 31
	s_nop 1
	s_lshl_b64 s[26:27], s[30:31], 19
	v_readlane_b32 s6, v253, 18
	v_readlane_b32 s7, v253, 19
	s_add_u32 s34, s6, s26
	s_addc_u32 s35, s7, s27
	s_cmp_eq_u32 s101, 2
	s_cselect_b32 s26, 0x40000, 0
	s_add_u32 s34, s34, s26
	s_addc_u32 s35, s35, 0
	s_and_b64 s[26:27], s[44:45], exec
	s_cselect_b32 s31, s35, s41
	s_cselect_b32 s80, s34, s40
	s_ashr_i32 s29, s28, 31
	s_lshl_b64 s[26:27], s[28:29], 19
	s_add_u32 s36, s48, s26
	s_addc_u32 s37, s49, s27
	s_and_b64 s[26:27], s[44:45], exec
	s_cselect_b32 s29, s37, s43
	s_cselect_b32 vcc_lo, s36, s42
	s_add_u32 s40, s40, 0x40080
	s_addc_u32 s41, s41, 0
	s_add_u32 s26, s42, 0x100
	v_mov_b32_e32 v0, 0
	s_addc_u32 s27, s43, 0
	s_mov_b32 s96, -2
	v_mov_b32_e32 v1, v0
	v_mov_b32_e32 v2, v0
	v_mov_b32_e32 v3, v0
	v_mov_b32_e32 v8, v0
	v_mov_b32_e32 v9, v0
	v_mov_b32_e32 v10, v0
	v_mov_b32_e32 v11, v0
	v_mov_b32_e32 v16, v0
	v_mov_b32_e32 v17, v0
	v_mov_b32_e32 v18, v0
	v_mov_b32_e32 v19, v0
	v_mov_b32_e32 v24, v0
	v_mov_b32_e32 v25, v0
	v_mov_b32_e32 v26, v0
	v_mov_b32_e32 v27, v0
	v_mov_b32_e32 v32, v0
	v_mov_b32_e32 v33, v0
	v_mov_b32_e32 v34, v0
	v_mov_b32_e32 v35, v0
	v_mov_b32_e32 v40, v0
	v_mov_b32_e32 v41, v0
	v_mov_b32_e32 v42, v0
	v_mov_b32_e32 v43, v0
	v_mov_b32_e32 v48, v0
	v_mov_b32_e32 v49, v0
	v_mov_b32_e32 v50, v0
	v_mov_b32_e32 v51, v0
	v_mov_b32_e32 v56, v0
	v_mov_b32_e32 v57, v0
	v_mov_b32_e32 v58, v0
	v_mov_b32_e32 v59, v0
	v_mov_b32_e32 v4, v0
	v_mov_b32_e32 v5, v0
	v_mov_b32_e32 v6, v0
	v_mov_b32_e32 v7, v0
	v_mov_b32_e32 v12, v0
	v_mov_b32_e32 v13, v0
	v_mov_b32_e32 v14, v0
	v_mov_b32_e32 v15, v0
	v_mov_b32_e32 v20, v0
	v_mov_b32_e32 v21, v0
	v_mov_b32_e32 v22, v0
	v_mov_b32_e32 v23, v0
	v_mov_b32_e32 v28, v0
	v_mov_b32_e32 v29, v0
	v_mov_b32_e32 v30, v0
	v_mov_b32_e32 v31, v0
	v_mov_b32_e32 v36, v0
	v_mov_b32_e32 v37, v0
	v_mov_b32_e32 v38, v0
	v_mov_b32_e32 v39, v0
	v_mov_b32_e32 v44, v0
	v_mov_b32_e32 v45, v0
	v_mov_b32_e32 v46, v0
	v_mov_b32_e32 v47, v0
	v_mov_b32_e32 v52, v0
	v_mov_b32_e32 v53, v0
	v_mov_b32_e32 v54, v0
	v_mov_b32_e32 v55, v0
	v_mov_b32_e32 v60, v0
	v_mov_b32_e32 v61, v0
	v_mov_b32_e32 v62, v0
	v_mov_b32_e32 v63, v0
	v_mov_b32_e32 v64, v0
	v_mov_b32_e32 v65, v0
	v_mov_b32_e32 v66, v0
	v_mov_b32_e32 v67, v0
	v_mov_b32_e32 v72, v0
	v_mov_b32_e32 v73, v0
	v_mov_b32_e32 v74, v0
	v_mov_b32_e32 v75, v0
	v_mov_b32_e32 v80, v0
	v_mov_b32_e32 v81, v0
	v_mov_b32_e32 v82, v0
	v_mov_b32_e32 v83, v0
	v_mov_b32_e32 v88, v0
	v_mov_b32_e32 v89, v0
	v_mov_b32_e32 v90, v0
	v_mov_b32_e32 v91, v0
	v_mov_b32_e32 v96, v0
	v_mov_b32_e32 v97, v0
	v_mov_b32_e32 v98, v0
	v_mov_b32_e32 v99, v0
	v_mov_b32_e32 v104, v0
	v_mov_b32_e32 v105, v0
	v_mov_b32_e32 v106, v0
	v_mov_b32_e32 v107, v0
	v_mov_b32_e32 v112, v0
	v_mov_b32_e32 v113, v0
	v_mov_b32_e32 v114, v0
	v_mov_b32_e32 v115, v0
	v_mov_b32_e32 v120, v0
	v_mov_b32_e32 v121, v0
	v_mov_b32_e32 v122, v0
	v_mov_b32_e32 v123, v0
	v_mov_b32_e32 v68, v0
	v_mov_b32_e32 v69, v0
	v_mov_b32_e32 v70, v0
	v_mov_b32_e32 v71, v0
	v_mov_b32_e32 v76, v0
	v_mov_b32_e32 v77, v0
	v_mov_b32_e32 v78, v0
	v_mov_b32_e32 v79, v0
	v_mov_b32_e32 v84, v0
	v_mov_b32_e32 v85, v0
	v_mov_b32_e32 v86, v0
	v_mov_b32_e32 v87, v0
	v_mov_b32_e32 v92, v0
	v_mov_b32_e32 v93, v0
	v_mov_b32_e32 v94, v0
	v_mov_b32_e32 v95, v0
	v_mov_b32_e32 v100, v0
	v_mov_b32_e32 v101, v0
	v_mov_b32_e32 v102, v0
	v_mov_b32_e32 v103, v0
	v_mov_b32_e32 v108, v0
	v_mov_b32_e32 v109, v0
	v_mov_b32_e32 v110, v0
	v_mov_b32_e32 v111, v0
	v_mov_b32_e32 v116, v0
	v_mov_b32_e32 v117, v0
	v_mov_b32_e32 v118, v0
	v_mov_b32_e32 v119, v0
	v_mov_b32_e32 v124, v0
	v_mov_b32_e32 v125, v0
	v_mov_b32_e32 v126, v0
	v_mov_b32_e32 v127, v0
	s_nop 1
	v_add_u32_e32 v230, 0x10000, v140

.Lmskip_94_6:
	s_barrier
	s_mov_b32 m0, s61
	v_lshl_add_u64 v[138:139], v[230:231], 0, s[24:25]
	global_load_lds_dwordx4 v[138:139], off
	v_lshl_add_u64 v[138:139], v[232:233], 0, s[24:25]
	s_mov_b32 m0, s62
	s_nop 0
	global_load_lds_dwordx4 v[138:139], off
	s_add_u32 s30, s30, 0x100
	s_addc_u32 s31, s31, 0
	s_add_u32 s26, s26, 0x100
	s_addc_u32 s27, s27, 0
	s_cmp_ge_u32 s71, s54
	s_mov_b32 s34, s71
	s_cbranch_scc0 .LBB0_94
	v_lshl_add_u32 v138, s69, 8, v140
	s_cmp_eq_u32 s100, 2
	s_cselect_b32 vcc_lo, 0x80, 0
	s_nop 0
	v_add_u32_e32 v138, vcc_lo, v138
	v_lshl_or_b32 v144, s70, 8, v143
	v_ashrrev_i32_e32 v139, 31, v138
	v_readlane_b32 s4, v253, 16
	v_ashrrev_i32_e32 v145, 31, v144
	v_cvt_pk_bf16_f32 v124, v124, v125
	v_cvt_pk_bf16_f32 v125, v126, v127
	v_cvt_pk_bf16_f32 v126, v120, v121
	v_lshlrev_b64 v[120:121], 11, v[138:139]
	v_readlane_b32 s5, v253, 17
	v_cvt_pk_bf16_f32 v127, v122, v123
	v_lshlrev_b64 v[122:123], 1, v[144:145]
	v_cvt_pk_bf16_f32 v116, v116, v117
	v_cvt_pk_bf16_f32 v117, v118, v119
	v_cvt_pk_bf16_f32 v119, v114, v115
	s_nop 0
	v_lshl_add_u64 v[120:121], s[4:5], 0, v[120:121]
	v_lshl_add_u64 v[120:121], v[120:121], 0, v[122:123]
	global_store_dwordx4 v[120:121], v[124:127], off
	v_or_b32_e32 v114, 32, v138
	v_cvt_pk_bf16_f32 v108, v108, v109
	v_cvt_pk_bf16_f32 v109, v110, v111
	v_cvt_pk_bf16_f32 v111, v106, v107
	v_or_b32_e32 v106, 48, v138
	v_or_b32_e32 v124, 16, v138
	v_cvt_pk_bf16_f32 v68, v68, v69
	v_cvt_pk_bf16_f32 v69, v70, v71
	v_cvt_pk_bf16_f32 v70, v64, v65
	v_add_u32_e32 v64, 0x80, v138
	v_cvt_pk_bf16_f32 v60, v60, v61
	v_cvt_pk_bf16_f32 v61, v62, v63
	v_cvt_pk_bf16_f32 v63, v58, v59
	v_add_u32_e32 v58, 0x90, v138
	v_cvt_pk_bf16_f32 v52, v52, v53
	v_cvt_pk_bf16_f32 v53, v54, v55
	v_cvt_pk_bf16_f32 v55, v50, v51
	v_add_u32_e32 v50, 0xa0, v138
	v_cvt_pk_bf16_f32 v44, v44, v45
	v_cvt_pk_bf16_f32 v45, v46, v47
	v_cvt_pk_bf16_f32 v47, v42, v43
	v_add_u32_e32 v42, 0xb0, v138
	v_ashrrev_i32_e32 v125, 31, v124
	v_ashrrev_i32_e32 v115, 31, v114
	v_ashrrev_i32_e32 v107, 31, v106
	v_ashrrev_i32_e32 v65, 31, v64
	v_ashrrev_i32_e32 v59, 31, v58
	v_ashrrev_i32_e32 v51, 31, v50
	v_ashrrev_i32_e32 v43, 31, v42
	v_cvt_pk_bf16_f32 v118, v112, v113
	v_lshlrev_b64 v[112:113], 11, v[124:125]
	v_cvt_pk_bf16_f32 v110, v104, v105
	v_lshlrev_b64 v[104:105], 11, v[114:115]
	v_cvt_pk_bf16_f32 v100, v100, v101
	v_cvt_pk_bf16_f32 v101, v102, v103
	v_cvt_pk_bf16_f32 v102, v96, v97
	v_lshlrev_b64 v[96:97], 11, v[106:107]
	v_cvt_pk_bf16_f32 v62, v56, v57
	v_lshlrev_b64 v[56:57], 11, v[64:65]
	v_cvt_pk_bf16_f32 v54, v48, v49
	v_lshlrev_b64 v[48:49], 11, v[58:59]
	v_cvt_pk_bf16_f32 v46, v40, v41
	v_lshlrev_b64 v[40:41], 11, v[50:51]
	v_cvt_pk_bf16_f32 v36, v36, v37
	v_cvt_pk_bf16_f32 v37, v38, v39
	v_cvt_pk_bf16_f32 v38, v32, v33
	v_lshlrev_b64 v[32:33], 11, v[42:43]
	v_lshl_add_u64 v[112:113], s[4:5], 0, v[112:113]
	v_lshl_add_u64 v[104:105], s[4:5], 0, v[104:105]
	v_lshl_add_u64 v[96:97], s[4:5], 0, v[96:97]
	v_lshl_add_u64 v[56:57], s[4:5], 0, v[56:57]
	v_lshl_add_u64 v[48:49], s[4:5], 0, v[48:49]
	v_lshl_add_u64 v[40:41], s[4:5], 0, v[40:41]
	v_lshl_add_u64 v[32:33], s[4:5], 0, v[32:33]
	v_lshl_add_u64 v[112:113], v[112:113], 0, v[122:123]
	v_lshl_add_u64 v[104:105], v[104:105], 0, v[122:123]
	v_lshl_add_u64 v[96:97], v[96:97], 0, v[122:123]
	v_lshl_add_u64 v[56:57], v[56:57], 0, v[122:123]
	v_lshl_add_u64 v[48:49], v[48:49], 0, v[122:123]
	v_lshl_add_u64 v[40:41], v[40:41], 0, v[122:123]
	v_lshl_add_u64 v[32:33], v[32:33], 0, v[122:123]
	s_and_b64 vcc, exec, s[22:23]
	s_mov_b32 s70, s65
	s_mov_b32 s69, s68
	s_mov_b64 s[34:35], s[0:1]
	s_mov_b64 s[30:31], s[28:29]
	s_mov_b32 s71, 0x42ce8ed0
	s_nop 1
	global_store_dwordx4 v[112:113], v[116:119], off
	global_store_dwordx4 v[104:105], v[108:111], off
	v_cvt_pk_bf16_f32 v103, v98, v99
	global_store_dwordx4 v[96:97], v[100:103], off
	v_cvt_pk_bf16_f32 v92, v92, v93
	v_cvt_pk_bf16_f32 v93, v94, v95
	v_cvt_pk_bf16_f32 v94, v88, v89
	v_cvt_pk_bf16_f32 v95, v90, v91
	global_store_dwordx4 v[120:121], v[92:95], off offset:256
	v_cvt_pk_bf16_f32 v84, v84, v85
	v_cvt_pk_bf16_f32 v85, v86, v87
	v_cvt_pk_bf16_f32 v86, v80, v81
	v_cvt_pk_bf16_f32 v87, v82, v83
	global_store_dwordx4 v[112:113], v[84:87], off offset:256
	v_cvt_pk_bf16_f32 v76, v76, v77
	v_cvt_pk_bf16_f32 v77, v78, v79
	v_cvt_pk_bf16_f32 v78, v72, v73
	v_cvt_pk_bf16_f32 v79, v74, v75
	global_store_dwordx4 v[104:105], v[76:79], off offset:256
	v_cvt_pk_bf16_f32 v71, v66, v67
	global_store_dwordx4 v[96:97], v[68:71], off offset:256
	s_cmp_lg_u32 s100, 0
	s_cbranch_scc1 .Lpjh_nost
	global_store_dwordx4 v[56:57], v[60:63], off
	global_store_dwordx4 v[48:49], v[52:55], off
	global_store_dwordx4 v[40:41], v[44:47], off
	v_cvt_pk_bf16_f32 v39, v34, v35
	global_store_dwordx4 v[32:33], v[36:39], off
	v_cvt_pk_bf16_f32 v28, v28, v29
	v_cvt_pk_bf16_f32 v29, v30, v31
	v_cvt_pk_bf16_f32 v30, v24, v25
	v_cvt_pk_bf16_f32 v31, v26, v27
	global_store_dwordx4 v[56:57], v[28:31], off offset:256
	v_cvt_pk_bf16_f32 v20, v20, v21
	v_cvt_pk_bf16_f32 v21, v22, v23
	v_cvt_pk_bf16_f32 v22, v16, v17
	v_cvt_pk_bf16_f32 v23, v18, v19
	global_store_dwordx4 v[48:49], v[20:23], off offset:256
	v_cvt_pk_bf16_f32 v12, v12, v13
	v_cvt_pk_bf16_f32 v13, v14, v15
	v_cvt_pk_bf16_f32 v14, v8, v9
	v_cvt_pk_bf16_f32 v15, v10, v11
	global_store_dwordx4 v[40:41], v[12:15], off offset:256
	v_cvt_pk_bf16_f32 v4, v4, v5
	v_cvt_pk_bf16_f32 v5, v6, v7
	v_cvt_pk_bf16_f32 v6, v0, v1
	v_cvt_pk_bf16_f32 v7, v2, v3
	global_store_dwordx4 v[32:33], v[4:7], off offset:256

.LBB0_232:
	v_readlane_b32 s28, v254, 26
	v_mov_b32_e32 v133, v185
	v_readlane_b32 s29, v254, 27
	v_mov_b32_e32 v129, v185
	v_readlane_b32 s22, v254, 22
	v_lshl_add_u64 v[8:9], s[28:29], 0, v[132:133]
	s_add_i32 s46, s38, 0x18000
	v_lshl_add_u64 v[10:11], s[28:29], 0, v[128:129]
	v_mov_b32_e32 v135, v185
	v_readlane_b32 s23, v254, 23
	v_lshl_add_u64 v[8:9], v[8:9], 0, s[24:25]
	s_mov_b32 m0, s46
	s_add_i32 s47, s38, 0x1a000
	v_lshl_add_u64 v[12:13], s[22:23], 0, v[134:135]
	v_mov_b32_e32 v131, v185
	s_waitcnt vmcnt(2)
	s_barrier
	global_load_lds_dwordx4 v[8:9], off
	v_lshl_add_u64 v[8:9], v[10:11], 0, s[24:25]
	s_mov_b32 m0, s47
	s_add_i32 s48, s38, 0x8000
	v_lshl_add_u64 v[14:15], s[22:23], 0, v[130:131]
	global_load_lds_dwordx4 v[8:9], off
	v_lshl_add_u64 v[8:9], v[12:13], 0, s[24:25]
	s_mov_b32 m0, s48
	s_add_i32 s49, s38, 0xa000
	v_readlane_b32 s4, v254, 28
	global_load_lds_dwordx4 v[8:9], off
	v_lshl_add_u64 v[8:9], v[14:15], 0, s[24:25]
	s_mov_b32 m0, s49
	s_add_i32 s50, s38, 0x1c000
	v_readlane_b32 s5, v254, 29
	global_load_lds_dwordx4 v[8:9], off
	s_nop 0
	v_lshl_add_u64 v[8:9], s[4:5], 0, v[132:133]
	s_mov_b32 m0, s50
	s_add_i32 s51, s38, 0x1e000
	global_load_lds_dwordx4 v[8:9], off
	v_lshl_add_u64 v[8:9], s[4:5], 0, v[128:129]
	s_mov_b32 m0, s51
	v_and_b32_e32 v10, 48, v0
	global_load_lds_dwordx4 v[8:9], off
	v_and_b32_e32 v8, 15, v0
	v_lshlrev_b32_e32 v0, 2, v0
	s_and_b32 s0, s0, 3
	v_lshl_or_b32 v7, v8, 6, v10
	s_lshl_b32 s20, s1, 13
	v_and_b32_e32 v0, 32, v0
	v_bitop3_b32 v142, v7, s20, v0 bitop3:0xde
	s_lshl_b32 s20, s0, 12
	v_bitop3_b32 v143, v7, s20, v0 bitop3:0xde
	v_lshlrev_b32_e32 v0, 16, v5
	v_and_b32_e32 v0, 0xfffe0000, v0
	v_lshl_add_u32 v0, v4, 13, v0
	v_and_b32_e32 v4, 1, v5
	v_lshl_or_b32 v0, v4, 6, v0
	v_lshl_add_u32 v136, v6, 1, v0
	v_lshlrev_b32_e32 v0, 16, v1
	s_lshl_b32 s0, s0, 6
	v_and_b32_e32 v0, 0xfffe0000, v0
	s_waitcnt vmcnt(6)
	s_lshl_b32 s52, s1, 2
	s_or_b32 s1, s0, 0x100
	v_lshl_add_u32 v0, v2, 13, v0
	v_and_b32_e32 v1, 1, v1
	v_lshl_or_b32 v0, v1, 6, v0
	s_lshl_b32 s63, s0, 4
	s_lshl_b32 s64, s1, 4
	v_readlane_b32 s0, v254, 18
	s_nop 1
	s_add_i32 s53, s52, 8
	s_or_b32 s54, s52, 1
	s_or_b32 s55, s52, 2
	s_or_b32 s58, s52, 3
	s_add_i32 s59, s52, 9
	s_add_i32 s60, s52, 10
	s_add_i32 s61, s52, 11
	v_mov_b32_e32 v137, v185
	v_lshl_add_u32 v138, v3, 1, v0
	v_mov_b32_e32 v139, v185
	s_mov_b32 s62, 0
	v_lshlrev_b32_e32 v184, 4, v10
	v_lshlrev_b32_e32 v140, 4, v8
	s_mov_b32 s71, s0
	v_readlane_b32 s70, v254, 16
	v_readlane_b32 s56, v254, 17
	v_readlane_b32 s78, v253, 22
	v_readlane_b32 s79, v253, 23
	s_barrier
	s_nop 1
.LBB0_233:
	s_add_i32 s62, s62, 1
	s_waitcnt lgkmcnt(0)
	s_mul_i32 s0, s62, s90
	s_mov_b64 s[26:27], s[22:23]
	s_add_i32 s22, s0, s96
	s_cmpk_lt_i32 s22, 0x100
	s_cselect_b64 s[30:31], -1, 0
	s_cmpk_gt_i32 s22, 0xff
	s_mov_b64 s[34:35], s[28:29]
	s_mov_b32 s20, s69
	s_mov_b32 s29, s68
	s_mov_b32 s28, s65
	s_cselect_b64 s[0:1], -1, 0
	s_and_b32 s68, s22, 3
	s_bfe_u32 s69, s22, 0x30002
	s_ashr_i32 s65, s22, 5
	s_and_b64 s[22:23], s[30:31], exec
	s_cselect_b32 s29, s68, s29
	s_cselect_b32 s28, s65, s28
	s_cselect_b32 s22, s69, s20
	s_lshl_b32 s36, s29, 10
	s_ashr_i32 s23, s22, 31
	s_ashr_i32 s37, s36, 31
	s_nop 1
	s_lshl_b64 s[22:23], s[22:23], 21
	s_lshl_b64 s[36:37], s[36:37], 1
	v_readlane_b32 s16, v253, 12
	v_readlane_b32 s17, v253, 13
	s_add_u32 s20, s16, s22
	s_addc_u32 s23, s17, s23
	s_add_u32 s22, s20, s36
	s_addc_u32 s23, s23, s37
	s_and_b64 vcc, s[30:31], exec
	s_cselect_b32 vcc_lo, s23, s27
	s_cselect_b32 vcc_hi, s22, s26
	s_ashr_i32 s29, s28, 31
	s_lshl_b64 s[28:29], s[28:29], 13
	s_add_u32 s20, s78, s28
	s_addc_u32 s29, s79, s29
	s_add_u32 s28, s20, s36
	s_addc_u32 s29, s29, s37
	s_and_b64 s[30:31], s[30:31], exec
	s_cselect_b32 s33, s29, s35
	s_cselect_b32 s20, s28, s34
	s_add_u32 s30, s26, 0x100080
	s_addc_u32 s31, s27, 0
	s_add_u32 s26, s34, 0x100
	v_mov_b32_e32 v0, 0
	s_addc_u32 s27, s35, 0
	s_mov_b32 s96, -2
	v_mov_b32_e32 v1, v0
	v_mov_b32_e32 v2, v0
	v_mov_b32_e32 v3, v0
	v_mov_b32_e32 v4, v0
	v_mov_b32_e32 v5, v0
	v_mov_b32_e32 v6, v0
	v_mov_b32_e32 v7, v0
	v_mov_b32_e32 v8, v0
	v_mov_b32_e32 v9, v0
	v_mov_b32_e32 v10, v0
	v_mov_b32_e32 v11, v0
	v_mov_b32_e32 v12, v0
	v_mov_b32_e32 v13, v0
	v_mov_b32_e32 v14, v0
	v_mov_b32_e32 v15, v0
	v_mov_b32_e32 v16, v0
	v_mov_b32_e32 v17, v0
	v_mov_b32_e32 v18, v0
	v_mov_b32_e32 v19, v0
	v_mov_b32_e32 v20, v0
	v_mov_b32_e32 v21, v0
	v_mov_b32_e32 v22, v0
	v_mov_b32_e32 v23, v0
	v_mov_b32_e32 v24, v0
	v_mov_b32_e32 v25, v0
	v_mov_b32_e32 v26, v0
	v_mov_b32_e32 v27, v0
	v_mov_b32_e32 v28, v0
	v_mov_b32_e32 v29, v0
	v_mov_b32_e32 v30, v0
	v_mov_b32_e32 v31, v0
	v_mov_b32_e32 v32, v0
	v_mov_b32_e32 v33, v0
	v_mov_b32_e32 v34, v0
	v_mov_b32_e32 v35, v0
	v_mov_b32_e32 v36, v0
	v_mov_b32_e32 v37, v0
	v_mov_b32_e32 v38, v0
	v_mov_b32_e32 v39, v0
	v_mov_b32_e32 v40, v0
	v_mov_b32_e32 v41, v0
	v_mov_b32_e32 v42, v0
	v_mov_b32_e32 v43, v0
	v_mov_b32_e32 v44, v0
	v_mov_b32_e32 v45, v0
	v_mov_b32_e32 v46, v0
	v_mov_b32_e32 v47, v0
	v_mov_b32_e32 v48, v0
	v_mov_b32_e32 v49, v0
	v_mov_b32_e32 v50, v0
	v_mov_b32_e32 v51, v0
	v_mov_b32_e32 v52, v0
	v_mov_b32_e32 v53, v0
	v_mov_b32_e32 v54, v0
	v_mov_b32_e32 v55, v0
	v_mov_b32_e32 v56, v0
	v_mov_b32_e32 v57, v0
	v_mov_b32_e32 v58, v0
	v_mov_b32_e32 v59, v0
	v_mov_b32_e32 v60, v0
	v_mov_b32_e32 v61, v0
	v_mov_b32_e32 v62, v0
	v_mov_b32_e32 v63, v0
	v_mov_b32_e32 v64, v0
	v_mov_b32_e32 v65, v0
	v_mov_b32_e32 v66, v0
	v_mov_b32_e32 v67, v0
	v_mov_b32_e32 v68, v0
	v_mov_b32_e32 v69, v0
	v_mov_b32_e32 v70, v0
	v_mov_b32_e32 v71, v0
	v_mov_b32_e32 v72, v0
	v_mov_b32_e32 v73, v0
	v_mov_b32_e32 v74, v0
	v_mov_b32_e32 v75, v0
	v_mov_b32_e32 v76, v0
	v_mov_b32_e32 v77, v0
	v_mov_b32_e32 v78, v0
	v_mov_b32_e32 v79, v0
	v_mov_b32_e32 v80, v0
	v_mov_b32_e32 v81, v0
	v_mov_b32_e32 v82, v0
	v_mov_b32_e32 v83, v0
	v_mov_b32_e32 v84, v0
	v_mov_b32_e32 v85, v0
	v_mov_b32_e32 v86, v0
	v_mov_b32_e32 v87, v0
	v_mov_b32_e32 v88, v0
	v_mov_b32_e32 v89, v0
	v_mov_b32_e32 v90, v0
	v_mov_b32_e32 v91, v0
	v_mov_b32_e32 v92, v0
	v_mov_b32_e32 v93, v0
	v_mov_b32_e32 v94, v0
	v_mov_b32_e32 v95, v0
	v_mov_b32_e32 v96, v0
	v_mov_b32_e32 v97, v0
	v_mov_b32_e32 v98, v0
	v_mov_b32_e32 v99, v0
	v_mov_b32_e32 v100, v0
	v_mov_b32_e32 v101, v0
	v_mov_b32_e32 v102, v0
	v_mov_b32_e32 v103, v0
	v_mov_b32_e32 v104, v0
	v_mov_b32_e32 v105, v0
	v_mov_b32_e32 v106, v0
	v_mov_b32_e32 v107, v0
	v_mov_b32_e32 v108, v0
	v_mov_b32_e32 v109, v0
	v_mov_b32_e32 v110, v0
	v_mov_b32_e32 v111, v0
	v_mov_b32_e32 v112, v0
	v_mov_b32_e32 v113, v0
	v_mov_b32_e32 v114, v0
	v_mov_b32_e32 v115, v0
	v_mov_b32_e32 v116, v0
	v_mov_b32_e32 v117, v0
	v_mov_b32_e32 v118, v0
	v_mov_b32_e32 v119, v0
	v_mov_b32_e32 v120, v0
	v_mov_b32_e32 v121, v0
	v_mov_b32_e32 v122, v0
	v_mov_b32_e32 v123, v0
	v_mov_b32_e32 v124, v0
	v_mov_b32_e32 v125, v0
	v_mov_b32_e32 v126, v0
	v_mov_b32_e32 v127, v0
	s_nop 1
	v_add_u32_e32 v230, 0x10000, v143
.LBB0_234:
	ds_read_b128 v[144:147], v230
	ds_read_b128 v[148:151], v230 offset:1024
	ds_read_b128 v[152:155], v230 offset:2048
	ds_read_b128 v[156:159], v230 offset:3072
	s_add_u32 s34, s30, 0xfff00080
	s_addc_u32 s35, s31, -1
	s_cmp_eq_u32 s96, 12
	s_cselect_b32 s37, vcc_lo, s35
	s_cselect_b32 s36, vcc_hi, s34
	s_cselect_b32 s35, s33, s27
	s_cselect_b32 s34, s20, s26
	v_lshl_add_u64 v[190:191], s[30:31], 0, v[136:137]
	s_add_i32 m0, s38, 0xc000
	ds_read_b128 v[160:163], v142
	ds_read_b128 v[164:167], v142 offset:1024
	ds_read_b128 v[168:171], v142 offset:2048
	ds_read_b128 v[172:175], v142 offset:3072
	ds_read_b128 v[176:179], v142 offset:4096
	ds_read_b128 v[180:183], v142 offset:5120
	ds_read_b128 v[186:189], v142 offset:6144
	ds_read_b128 v[194:197], v142 offset:7168
	global_load_lds_dwordx4 v[190:191], off
	v_lshl_add_u64 v[190:191], s[30:31], 0, v[138:139]
	s_add_i32 m0, s38, 0xe000
	s_nop 0
	global_load_lds_dwordx4 v[190:191], off
	ds_read_b128 v[198:201], v230 offset:16384
	ds_read_b128 v[202:205], v230 offset:17408
	ds_read_b128 v[206:209], v230 offset:18432
	ds_read_b128 v[210:213], v230 offset:19456
	s_waitcnt vmcnt(8) lgkmcnt(0)
	s_barrier
	v_mfma_f32_16x16x32_bf16 v[124:127], v[144:147], v[160:163], v[124:127]
	v_mfma_f32_16x16x32_bf16 v[120:123], v[152:155], v[160:163], v[120:123]
	v_mfma_f32_16x16x32_bf16 v[116:119], v[144:147], v[168:171], v[116:119]
	v_mfma_f32_16x16x32_bf16 v[112:115], v[152:155], v[168:171], v[112:115]
	v_mfma_f32_16x16x32_bf16 v[108:111], v[144:147], v[176:179], v[108:111]
	v_mfma_f32_16x16x32_bf16 v[104:107], v[152:155], v[176:179], v[104:107]
	v_mfma_f32_16x16x32_bf16 v[100:103], v[144:147], v[186:189], v[100:103]
	v_mfma_f32_16x16x32_bf16 v[96:99], v[152:155], v[186:189], v[96:99]
	v_mfma_f32_16x16x32_bf16 v[124:127], v[148:151], v[164:167], v[124:127]
	v_mfma_f32_16x16x32_bf16 v[120:123], v[156:159], v[164:167], v[120:123]
	v_mfma_f32_16x16x32_bf16 v[116:119], v[148:151], v[172:175], v[116:119]
	v_mfma_f32_16x16x32_bf16 v[112:115], v[156:159], v[172:175], v[112:115]
	v_mfma_f32_16x16x32_bf16 v[108:111], v[148:151], v[180:183], v[108:111]
	v_mfma_f32_16x16x32_bf16 v[104:107], v[156:159], v[180:183], v[104:107]
	v_mfma_f32_16x16x32_bf16 v[100:103], v[148:151], v[194:197], v[100:103]
	v_mfma_f32_16x16x32_bf16 v[96:99], v[156:159], v[194:197], v[96:99]
	v_mfma_f32_16x16x32_bf16 v[92:95], v[198:201], v[160:163], v[92:95]
	v_mfma_f32_16x16x32_bf16 v[88:91], v[206:209], v[160:163], v[88:91]
	v_mfma_f32_16x16x32_bf16 v[84:87], v[198:201], v[168:171], v[84:87]
	v_mfma_f32_16x16x32_bf16 v[80:83], v[206:209], v[168:171], v[80:83]
	v_mfma_f32_16x16x32_bf16 v[76:79], v[198:201], v[176:179], v[76:79]
	v_mfma_f32_16x16x32_bf16 v[72:75], v[206:209], v[176:179], v[72:75]
	v_mfma_f32_16x16x32_bf16 v[68:71], v[198:201], v[186:189], v[68:71]
	v_mfma_f32_16x16x32_bf16 v[64:67], v[206:209], v[186:189], v[64:67]
	v_mfma_f32_16x16x32_bf16 v[92:95], v[202:205], v[164:167], v[92:95]
	v_mfma_f32_16x16x32_bf16 v[88:91], v[210:213], v[164:167], v[88:91]
	v_mfma_f32_16x16x32_bf16 v[84:87], v[202:205], v[172:175], v[84:87]
	v_mfma_f32_16x16x32_bf16 v[80:83], v[210:213], v[172:175], v[80:83]
	v_mfma_f32_16x16x32_bf16 v[76:79], v[202:205], v[180:183], v[76:79]
	v_mfma_f32_16x16x32_bf16 v[72:75], v[210:213], v[180:183], v[72:75]
	v_mfma_f32_16x16x32_bf16 v[68:71], v[202:205], v[194:197], v[68:71]
	v_mfma_f32_16x16x32_bf16 v[64:67], v[210:213], v[194:197], v[64:67]
	s_barrier
	s_mov_b32 m0, s39
	v_lshl_add_u64 v[190:191], s[34:35], 0, v[132:133]
	global_load_lds_dwordx4 v[190:191], off
	v_lshl_add_u64 v[214:215], s[34:35], 0, v[128:129]
	s_mov_b32 m0, s40
	s_nop 0
	global_load_lds_dwordx4 v[214:215], off
	s_mov_b32 m0, s38
	v_lshl_add_u64 v[216:217], s[36:37], 0, v[134:135]
	ds_read_b128 v[160:163], v142 offset:16384
	ds_read_b128 v[164:167], v142 offset:17408
	ds_read_b128 v[168:171], v142 offset:18432
	ds_read_b128 v[172:175], v142 offset:19456
	ds_read_b128 v[176:179], v142 offset:20480
	ds_read_b128 v[180:183], v142 offset:21504
	ds_read_b128 v[186:189], v142 offset:22528
	ds_read_b128 v[194:197], v142 offset:23552
	global_load_lds_dwordx4 v[216:217], off
	v_lshl_add_u64 v[242:243], s[36:37], 0, v[130:131]
	s_mov_b32 m0, s41
	s_nop 0
	global_load_lds_dwordx4 v[242:243], off
	s_waitcnt vmcnt(6) lgkmcnt(0)
	s_barrier
	v_mfma_f32_16x16x32_bf16 v[60:63], v[144:147], v[160:163], v[60:63]
	v_mfma_f32_16x16x32_bf16 v[56:59], v[152:155], v[160:163], v[56:59]
	v_mfma_f32_16x16x32_bf16 v[52:55], v[144:147], v[168:171], v[52:55]
	v_mfma_f32_16x16x32_bf16 v[48:51], v[152:155], v[168:171], v[48:51]
	v_mfma_f32_16x16x32_bf16 v[44:47], v[144:147], v[176:179], v[44:47]
	v_mfma_f32_16x16x32_bf16 v[40:43], v[152:155], v[176:179], v[40:43]
	v_mfma_f32_16x16x32_bf16 v[36:39], v[144:147], v[186:189], v[36:39]
	v_mfma_f32_16x16x32_bf16 v[32:35], v[152:155], v[186:189], v[32:35]
	v_mfma_f32_16x16x32_bf16 v[60:63], v[148:151], v[164:167], v[60:63]
	v_mfma_f32_16x16x32_bf16 v[56:59], v[156:159], v[164:167], v[56:59]
	v_mfma_f32_16x16x32_bf16 v[52:55], v[148:151], v[172:175], v[52:55]
	v_mfma_f32_16x16x32_bf16 v[48:51], v[156:159], v[172:175], v[48:51]
	v_mfma_f32_16x16x32_bf16 v[44:47], v[148:151], v[180:183], v[44:47]
	v_mfma_f32_16x16x32_bf16 v[40:43], v[156:159], v[180:183], v[40:43]
	v_mfma_f32_16x16x32_bf16 v[36:39], v[148:151], v[194:197], v[36:39]
	v_mfma_f32_16x16x32_bf16 v[32:35], v[156:159], v[194:197], v[32:35]
	v_mfma_f32_16x16x32_bf16 v[28:31], v[198:201], v[160:163], v[28:31]
	v_mfma_f32_16x16x32_bf16 v[24:27], v[206:209], v[160:163], v[24:27]
	v_mfma_f32_16x16x32_bf16 v[20:23], v[198:201], v[168:171], v[20:23]
	v_mfma_f32_16x16x32_bf16 v[16:19], v[206:209], v[168:171], v[16:19]
	v_mfma_f32_16x16x32_bf16 v[12:15], v[198:201], v[176:179], v[12:15]
	v_mfma_f32_16x16x32_bf16 v[8:11], v[206:209], v[176:179], v[8:11]
	v_mfma_f32_16x16x32_bf16 v[4:7], v[198:201], v[186:189], v[4:7]
	v_mfma_f32_16x16x32_bf16 v[0:3], v[206:209], v[186:189], v[0:3]
	v_mfma_f32_16x16x32_bf16 v[28:31], v[202:205], v[164:167], v[28:31]
	v_mfma_f32_16x16x32_bf16 v[24:27], v[210:213], v[164:167], v[24:27]
	v_mfma_f32_16x16x32_bf16 v[20:23], v[202:205], v[172:175], v[20:23]
	v_mfma_f32_16x16x32_bf16 v[16:19], v[210:213], v[172:175], v[16:19]
	v_mfma_f32_16x16x32_bf16 v[12:15], v[202:205], v[180:183], v[12:15]
	v_mfma_f32_16x16x32_bf16 v[8:11], v[210:213], v[180:183], v[8:11]
	v_mfma_f32_16x16x32_bf16 v[4:7], v[202:205], v[194:197], v[4:7]
	v_mfma_f32_16x16x32_bf16 v[0:3], v[210:213], v[194:197], v[0:3]
	s_barrier
	s_add_u32 s66, s34, 0x800000
	s_addc_u32 s67, s35, 0
	s_mov_b32 m0, s42
	v_lshl_add_u64 v[144:145], s[66:67], 0, v[132:133]
	global_load_lds_dwordx4 v[144:145], off
	v_lshl_add_u64 v[144:145], s[66:67], 0, v[128:129]
	s_mov_b32 m0, s43
	s_nop 0
	global_load_lds_dwordx4 v[144:145], off
	ds_read_b128 v[144:147], v230 offset:32768
	ds_read_b128 v[148:151], v230 offset:33792
	ds_read_b128 v[152:155], v230 offset:34816
	ds_read_b128 v[156:159], v230 offset:35840
	s_add_u32 s36, s36, 0x100000
	s_addc_u32 s37, s37, 0
	s_mov_b32 m0, s44
	v_lshl_add_u64 v[198:199], s[36:37], 0, v[134:135]
	ds_read_b128 v[160:163], v142 offset:32768
	ds_read_b128 v[164:167], v142 offset:33792
	ds_read_b128 v[168:171], v142 offset:34816
	ds_read_b128 v[172:175], v142 offset:35840
	ds_read_b128 v[176:179], v142 offset:36864
	ds_read_b128 v[180:183], v142 offset:37888
	ds_read_b128 v[186:189], v142 offset:38912
	ds_read_b128 v[194:197], v142 offset:39936
	global_load_lds_dwordx4 v[198:199], off
	v_lshl_add_u64 v[198:199], s[36:37], 0, v[130:131]
	s_mov_b32 m0, s45
	s_nop 0
	global_load_lds_dwordx4 v[198:199], off
	ds_read_b128 v[198:201], v230 offset:49152
	ds_read_b128 v[202:205], v230 offset:50176
	ds_read_b128 v[206:209], v230 offset:51200
	ds_read_b128 v[210:213], v230 offset:52224
	s_waitcnt vmcnt(8) lgkmcnt(0)
	s_barrier
	v_mfma_f32_16x16x32_bf16 v[124:127], v[144:147], v[160:163], v[124:127]
	v_mfma_f32_16x16x32_bf16 v[120:123], v[152:155], v[160:163], v[120:123]
	v_mfma_f32_16x16x32_bf16 v[116:119], v[144:147], v[168:171], v[116:119]
	v_mfma_f32_16x16x32_bf16 v[112:115], v[152:155], v[168:171], v[112:115]
	v_mfma_f32_16x16x32_bf16 v[108:111], v[144:147], v[176:179], v[108:111]
	v_mfma_f32_16x16x32_bf16 v[104:107], v[152:155], v[176:179], v[104:107]
	v_mfma_f32_16x16x32_bf16 v[100:103], v[144:147], v[186:189], v[100:103]
	v_mfma_f32_16x16x32_bf16 v[96:99], v[152:155], v[186:189], v[96:99]
	v_mfma_f32_16x16x32_bf16 v[124:127], v[148:151], v[164:167], v[124:127]
	v_mfma_f32_16x16x32_bf16 v[120:123], v[156:159], v[164:167], v[120:123]
	v_mfma_f32_16x16x32_bf16 v[116:119], v[148:151], v[172:175], v[116:119]
	v_mfma_f32_16x16x32_bf16 v[112:115], v[156:159], v[172:175], v[112:115]
	v_mfma_f32_16x16x32_bf16 v[108:111], v[148:151], v[180:183], v[108:111]
	v_mfma_f32_16x16x32_bf16 v[104:107], v[156:159], v[180:183], v[104:107]
	v_mfma_f32_16x16x32_bf16 v[100:103], v[148:151], v[194:197], v[100:103]
	v_mfma_f32_16x16x32_bf16 v[96:99], v[156:159], v[194:197], v[96:99]
	v_mfma_f32_16x16x32_bf16 v[92:95], v[198:201], v[160:163], v[92:95]
	v_mfma_f32_16x16x32_bf16 v[88:91], v[206:209], v[160:163], v[88:91]
	v_mfma_f32_16x16x32_bf16 v[84:87], v[198:201], v[168:171], v[84:87]
	v_mfma_f32_16x16x32_bf16 v[80:83], v[206:209], v[168:171], v[80:83]
	v_mfma_f32_16x16x32_bf16 v[76:79], v[198:201], v[176:179], v[76:79]
	v_mfma_f32_16x16x32_bf16 v[72:75], v[206:209], v[176:179], v[72:75]
	v_mfma_f32_16x16x32_bf16 v[68:71], v[198:201], v[186:189], v[68:71]
	v_mfma_f32_16x16x32_bf16 v[64:67], v[206:209], v[186:189], v[64:67]
	v_mfma_f32_16x16x32_bf16 v[92:95], v[202:205], v[164:167], v[92:95]
	v_mfma_f32_16x16x32_bf16 v[88:91], v[210:213], v[164:167], v[88:91]
	v_mfma_f32_16x16x32_bf16 v[84:87], v[202:205], v[172:175], v[84:87]
	v_mfma_f32_16x16x32_bf16 v[80:83], v[210:213], v[172:175], v[80:83]
	v_mfma_f32_16x16x32_bf16 v[76:79], v[202:205], v[180:183], v[76:79]
	v_mfma_f32_16x16x32_bf16 v[72:75], v[210:213], v[180:183], v[72:75]
	v_mfma_f32_16x16x32_bf16 v[68:71], v[202:205], v[194:197], v[68:71]
	v_mfma_f32_16x16x32_bf16 v[64:67], v[210:213], v[194:197], v[64:67]
	s_barrier
	s_mov_b32 m0, s46
	v_lshl_add_u64 v[190:191], v[190:191], 0, s[24:25]
	global_load_lds_dwordx4 v[190:191], off
	v_lshl_add_u64 v[190:191], v[214:215], 0, s[24:25]
	s_mov_b32 m0, s47
	s_nop 0
	global_load_lds_dwordx4 v[190:191], off
	s_mov_b32 m0, s48
	v_lshl_add_u64 v[190:191], v[216:217], 0, s[24:25]
	ds_read_b128 v[160:163], v142 offset:49152
	ds_read_b128 v[164:167], v142 offset:50176
	ds_read_b128 v[168:171], v142 offset:51200
	ds_read_b128 v[172:175], v142 offset:52224
	ds_read_b128 v[176:179], v142 offset:53248
	ds_read_b128 v[180:183], v142 offset:54272
	ds_read_b128 v[186:189], v142 offset:55296
	ds_read_b128 v[194:197], v142 offset:56320
	global_load_lds_dwordx4 v[190:191], off
	v_lshl_add_u64 v[190:191], v[242:243], 0, s[24:25]
	s_mov_b32 m0, s49
	s_nop 0
	global_load_lds_dwordx4 v[190:191], off
	s_waitcnt vmcnt(6) lgkmcnt(0)
	s_barrier
	v_mfma_f32_16x16x32_bf16 v[60:63], v[144:147], v[160:163], v[60:63]
	v_mfma_f32_16x16x32_bf16 v[56:59], v[152:155], v[160:163], v[56:59]
	v_mfma_f32_16x16x32_bf16 v[52:55], v[144:147], v[168:171], v[52:55]
	v_mfma_f32_16x16x32_bf16 v[48:51], v[152:155], v[168:171], v[48:51]
	v_mfma_f32_16x16x32_bf16 v[44:47], v[144:147], v[176:179], v[44:47]
	v_mfma_f32_16x16x32_bf16 v[40:43], v[152:155], v[176:179], v[40:43]
	v_mfma_f32_16x16x32_bf16 v[36:39], v[144:147], v[186:189], v[36:39]
	v_mfma_f32_16x16x32_bf16 v[32:35], v[152:155], v[186:189], v[32:35]
	v_mfma_f32_16x16x32_bf16 v[60:63], v[148:151], v[164:167], v[60:63]
	v_mfma_f32_16x16x32_bf16 v[56:59], v[156:159], v[164:167], v[56:59]
	v_mfma_f32_16x16x32_bf16 v[52:55], v[148:151], v[172:175], v[52:55]
	v_mfma_f32_16x16x32_bf16 v[48:51], v[156:159], v[172:175], v[48:51]
	v_mfma_f32_16x16x32_bf16 v[44:47], v[148:151], v[180:183], v[44:47]
	v_mfma_f32_16x16x32_bf16 v[40:43], v[156:159], v[180:183], v[40:43]
	v_mfma_f32_16x16x32_bf16 v[36:39], v[148:151], v[194:197], v[36:39]
	v_mfma_f32_16x16x32_bf16 v[32:35], v[156:159], v[194:197], v[32:35]
	v_mfma_f32_16x16x32_bf16 v[28:31], v[198:201], v[160:163], v[28:31]
	v_mfma_f32_16x16x32_bf16 v[24:27], v[206:209], v[160:163], v[24:27]
	v_mfma_f32_16x16x32_bf16 v[20:23], v[198:201], v[168:171], v[20:23]
	v_mfma_f32_16x16x32_bf16 v[16:19], v[206:209], v[168:171], v[16:19]
	v_mfma_f32_16x16x32_bf16 v[12:15], v[198:201], v[176:179], v[12:15]
	v_mfma_f32_16x16x32_bf16 v[8:11], v[206:209], v[176:179], v[8:11]
	v_mfma_f32_16x16x32_bf16 v[4:7], v[198:201], v[186:189], v[4:7]
	v_mfma_f32_16x16x32_bf16 v[0:3], v[206:209], v[186:189], v[0:3]
	v_mfma_f32_16x16x32_bf16 v[28:31], v[202:205], v[164:167], v[28:31]
	v_mfma_f32_16x16x32_bf16 v[24:27], v[210:213], v[164:167], v[24:27]
	v_mfma_f32_16x16x32_bf16 v[20:23], v[202:205], v[172:175], v[20:23]
	v_mfma_f32_16x16x32_bf16 v[16:19], v[210:213], v[172:175], v[16:19]
	v_mfma_f32_16x16x32_bf16 v[12:15], v[202:205], v[180:183], v[12:15]
	v_mfma_f32_16x16x32_bf16 v[8:11], v[210:213], v[180:183], v[8:11]
	v_mfma_f32_16x16x32_bf16 v[4:7], v[202:205], v[194:197], v[4:7]
	v_mfma_f32_16x16x32_bf16 v[0:3], v[210:213], v[194:197], v[0:3]
	s_barrier
	s_add_u32 s34, s34, 0x800080
	s_addc_u32 s35, s35, 0
	s_mov_b32 m0, s50
	v_lshl_add_u64 v[144:145], s[34:35], 0, v[132:133]
	global_load_lds_dwordx4 v[144:145], off
	v_lshl_add_u64 v[144:145], s[34:35], 0, v[128:129]
	s_mov_b32 m0, s51
	s_nop 0
	global_load_lds_dwordx4 v[144:145], off
	s_add_i32 s96, s96, 2
	s_add_u32 s30, s30, 0x100
	s_addc_u32 s31, s31, 0
	s_add_u32 s26, s26, 0x100
	s_addc_u32 s27, s27, 0
	s_cmp_gt_u32 s96, 13
	s_cbranch_scc0 .LBB0_234
	s_lshl_b32 s20, s71, 7
	s_lshl_b32 s26, s56, 4
	s_or_b32 s27, s26, s20
	s_add_i32 s34, s27, s52
	s_lshl_b32 s88, s70, 19
	s_nop 1
	s_ashr_i32 s35, s34, 31
	s_lshl_b64 s[30:31], s[88:89], 4
	v_readlane_b32 s74, v253, 18
	v_readlane_b32 s75, v253, 19
	s_add_u32 s27, s74, s30
	s_addc_u32 s30, s75, s31
	s_lshl_b64 s[34:35], s[34:35], 13
	s_add_u32 s31, s27, s34
	s_addc_u32 s33, s30, s35
	s_add_u32 s34, s31, s63
	s_addc_u32 s35, s33, 0
	v_cvt_pk_bf16_f32 v124, v124, v125
	v_cvt_pk_bf16_f32 v125, v126, v127
	v_cvt_pk_bf16_f32 v126, v120, v121
	v_lshl_add_u64 v[120:121], s[34:35], 0, v[184:185]
	s_add_i32 s34, s54, s20
	s_add_i32 s34, s34, s26
	s_ashr_i32 s35, s34, 31
	s_lshl_b64 s[34:35], s[34:35], 13
	s_add_u32 s36, s27, s34
	s_addc_u32 s37, s30, s35
	s_add_u32 s34, s36, s63
	s_addc_u32 s35, s37, 0
	v_cvt_pk_bf16_f32 v116, v116, v117
	v_cvt_pk_bf16_f32 v117, v118, v119
	v_cvt_pk_bf16_f32 v118, v112, v113
	v_lshl_add_u64 v[112:113], s[34:35], 0, v[184:185]
	s_add_i32 s34, s55, s20
	s_add_i32 s34, s34, s26
	s_ashr_i32 s35, s34, 31
	s_lshl_b64 s[34:35], s[34:35], 13
	s_add_u32 s66, s27, s34
	s_addc_u32 s67, s30, s35
	s_add_u32 s34, s66, s63
	s_addc_u32 s35, s67, 0
	v_cvt_pk_bf16_f32 v108, v108, v109
	v_cvt_pk_bf16_f32 v109, v110, v111
	v_cvt_pk_bf16_f32 v110, v104, v105
	v_lshl_add_u64 v[104:105], s[34:35], 0, v[184:185]
	s_add_i32 s34, s58, s20
	s_add_i32 s34, s34, s26
	s_ashr_i32 s35, s34, 31
	s_lshl_b64 s[34:35], s[34:35], 13
	s_add_u32 s70, s27, s34
	s_addc_u32 s71, s30, s35
	s_add_u32 s34, s70, s63
	s_addc_u32 s35, s71, 0
	v_cvt_pk_bf16_f32 v100, v100, v101
	v_cvt_pk_bf16_f32 v101, v102, v103
	v_cvt_pk_bf16_f32 v102, v96, v97
	v_lshl_add_u64 v[96:97], s[34:35], 0, v[184:185]
	s_add_u32 s34, s31, s64
	s_addc_u32 s35, s33, 0
	v_cvt_pk_bf16_f32 v92, v92, v93
	v_cvt_pk_bf16_f32 v93, v94, v95
	v_cvt_pk_bf16_f32 v94, v88, v89
	v_lshl_add_u64 v[88:89], s[34:35], 0, v[184:185]
	s_add_u32 s34, s36, s64
	s_addc_u32 s35, s37, 0
	v_cvt_pk_bf16_f32 v84, v84, v85
	v_cvt_pk_bf16_f32 v85, v86, v87
	v_cvt_pk_bf16_f32 v86, v80, v81
	v_lshl_add_u64 v[80:81], s[34:35], 0, v[184:185]
	s_add_u32 s34, s66, s64
	s_addc_u32 s35, s67, 0
	v_cvt_pk_bf16_f32 v76, v76, v77
	v_cvt_pk_bf16_f32 v77, v78, v79
	v_cvt_pk_bf16_f32 v78, v72, v73
	v_lshl_add_u64 v[72:73], s[34:35], 0, v[184:185]
	s_add_u32 s34, s70, s64
	s_addc_u32 s35, s71, 0
	s_add_i32 s31, s53, s20
	v_cvt_pk_bf16_f32 v68, v68, v69
	v_cvt_pk_bf16_f32 v69, v70, v71
	v_cvt_pk_bf16_f32 v70, v64, v65
	v_lshl_add_u64 v[64:65], s[34:35], 0, v[184:185]
	s_add_i32 s34, s31, s26
	s_ashr_i32 s35, s34, 31
	s_lshl_b64 s[34:35], s[34:35], 13
	s_add_u32 s31, s27, s34
	s_addc_u32 s33, s30, s35
	s_add_u32 s34, s31, s63
	s_addc_u32 s35, s33, 0
	v_cvt_pk_bf16_f32 v60, v60, v61
	v_cvt_pk_bf16_f32 v61, v62, v63
	v_cvt_pk_bf16_f32 v62, v56, v57
	v_lshl_add_u64 v[56:57], s[34:35], 0, v[184:185]
	s_add_i32 s34, s59, s20
	s_add_i32 s34, s34, s26
	s_ashr_i32 s35, s34, 31
	s_lshl_b64 s[34:35], s[34:35], 13
	s_add_u32 s36, s27, s34
	s_addc_u32 s37, s30, s35
	s_add_u32 s34, s36, s63
	s_addc_u32 s35, s37, 0
	v_cvt_pk_bf16_f32 v52, v52, v53
	v_cvt_pk_bf16_f32 v53, v54, v55
	v_cvt_pk_bf16_f32 v54, v48, v49
	v_lshl_add_u64 v[48:49], s[34:35], 0, v[184:185]
	s_add_i32 s34, s60, s20
	s_add_i32 s34, s34, s26
	s_ashr_i32 s35, s34, 31
	s_lshl_b64 s[34:35], s[34:35], 13
	s_add_u32 s66, s27, s34
	s_addc_u32 s67, s30, s35
	s_add_u32 s34, s66, s63
	s_addc_u32 s35, s67, 0
	s_add_i32 s20, s61, s20
	v_cvt_pk_bf16_f32 v44, v44, v45
	v_cvt_pk_bf16_f32 v45, v46, v47
	v_cvt_pk_bf16_f32 v46, v40, v41
	v_lshl_add_u64 v[40:41], s[34:35], 0, v[184:185]
	s_add_i32 s34, s20, s26
	s_ashr_i32 s35, s34, 31
	s_lshl_b64 s[34:35], s[34:35], 13
	s_add_u32 s20, s27, s34
	s_addc_u32 s30, s30, s35
	s_add_u32 s26, s20, s63
	s_addc_u32 s27, s30, 0
	v_cvt_pk_bf16_f32 v36, v36, v37
	v_cvt_pk_bf16_f32 v37, v38, v39
	v_cvt_pk_bf16_f32 v38, v32, v33
	v_lshl_add_u64 v[32:33], s[26:27], 0, v[184:185]
	s_add_u32 s26, s31, s64
	s_addc_u32 s27, s33, 0
	v_cvt_pk_bf16_f32 v28, v28, v29
	v_cvt_pk_bf16_f32 v29, v30, v31
	v_cvt_pk_bf16_f32 v30, v24, v25
	v_lshl_add_u64 v[24:25], s[26:27], 0, v[184:185]
	s_add_u32 s26, s36, s64
	s_addc_u32 s27, s37, 0
	v_cvt_pk_bf16_f32 v20, v20, v21
	v_cvt_pk_bf16_f32 v21, v22, v23
	v_cvt_pk_bf16_f32 v22, v16, v17
	v_lshl_add_u64 v[16:17], s[26:27], 0, v[184:185]
	s_add_u32 s26, s66, s64
	s_addc_u32 s27, s67, 0
	v_cvt_pk_bf16_f32 v12, v12, v13
	v_cvt_pk_bf16_f32 v13, v14, v15
	v_cvt_pk_bf16_f32 v14, v8, v9
	v_lshl_add_u64 v[8:9], s[26:27], 0, v[184:185]
	s_add_u32 s26, s20, s64
	s_addc_u32 s27, s30, 0
	v_mov_b32_e32 v141, v185
	v_cvt_pk_bf16_f32 v4, v4, v5
	v_cvt_pk_bf16_f32 v5, v6, v7
	v_cvt_pk_bf16_f32 v6, v0, v1
	v_lshl_add_u64 v[0:1], s[26:27], 0, v[184:185]
	v_readlane_b32 s78, v253, 22
	v_readlane_b32 s79, v253, 23
	v_lshl_add_u64 v[120:121], v[120:121], 0, v[140:141]
	v_lshl_add_u64 v[112:113], v[112:113], 0, v[140:141]
	v_lshl_add_u64 v[104:105], v[104:105], 0, v[140:141]
	v_lshl_add_u64 v[96:97], v[96:97], 0, v[140:141]
	v_lshl_add_u64 v[88:89], v[88:89], 0, v[140:141]
	v_lshl_add_u64 v[80:81], v[80:81], 0, v[140:141]
	v_lshl_add_u64 v[72:73], v[72:73], 0, v[140:141]
	v_lshl_add_u64 v[64:65], v[64:65], 0, v[140:141]
	v_lshl_add_u64 v[56:57], v[56:57], 0, v[140:141]
	v_lshl_add_u64 v[48:49], v[48:49], 0, v[140:141]
	v_lshl_add_u64 v[40:41], v[40:41], 0, v[140:141]
	v_lshl_add_u64 v[32:33], v[32:33], 0, v[140:141]
	v_lshl_add_u64 v[24:25], v[24:25], 0, v[140:141]
	v_lshl_add_u64 v[16:17], v[16:17], 0, v[140:141]
	v_lshl_add_u64 v[8:9], v[8:9], 0, v[140:141]
	v_lshl_add_u64 v[0:1], v[0:1], 0, v[140:141]
	s_and_b64 vcc, exec, s[0:1]
	s_mov_b32 s71, s65
	s_mov_b32 s70, s68
	s_mov_b32 s56, s69
	v_readlane_b32 s96, v255, 22
	v_cvt_pk_bf16_f32 v127, v122, v123
	s_nop 1
	global_store_dwordx4 v[120:121], v[124:127], off
	v_cvt_pk_bf16_f32 v119, v114, v115
	global_store_dwordx4 v[112:113], v[116:119], off
	v_cvt_pk_bf16_f32 v111, v106, v107
	global_store_dwordx4 v[104:105], v[108:111], off
	v_cvt_pk_bf16_f32 v103, v98, v99
	global_store_dwordx4 v[96:97], v[100:103], off
	v_cvt_pk_bf16_f32 v95, v90, v91
	global_store_dwordx4 v[88:89], v[92:95], off
	v_cvt_pk_bf16_f32 v87, v82, v83
	global_store_dwordx4 v[80:81], v[84:87], off
	v_cvt_pk_bf16_f32 v79, v74, v75
	global_store_dwordx4 v[72:73], v[76:79], off
	v_cvt_pk_bf16_f32 v71, v66, v67
	global_store_dwordx4 v[64:65], v[68:71], off
	v_cvt_pk_bf16_f32 v63, v58, v59
	global_store_dwordx4 v[56:57], v[60:63], off
	v_cvt_pk_bf16_f32 v55, v50, v51
	global_store_dwordx4 v[48:49], v[52:55], off
	v_cvt_pk_bf16_f32 v47, v42, v43
	global_store_dwordx4 v[40:41], v[44:47], off
	v_cvt_pk_bf16_f32 v39, v34, v35
	global_store_dwordx4 v[32:33], v[36:39], off
	v_cvt_pk_bf16_f32 v31, v26, v27
	global_store_dwordx4 v[24:25], v[28:31], off
	v_cvt_pk_bf16_f32 v23, v18, v19
	global_store_dwordx4 v[16:17], v[20:23], off
	v_cvt_pk_bf16_f32 v15, v10, v11
	global_store_dwordx4 v[8:9], v[12:15], off
	v_cvt_pk_bf16_f32 v7, v2, v3
	global_store_dwordx4 v[0:1], v[4:7], off
	s_cbranch_vccz .LBB0_233
	v_readlane_b32 s84, v255, 43
	s_waitcnt vmcnt(0)
	s_nop 1
	v_readlane_b32 s72, v255, 23
	v_readlane_b32 s86, v255, 31
	s_cmpk_gt_u32 s93, 0xff
	v_readlane_b32 s85, v255, 44
	v_readlane_b32 s73, v255, 24
	v_readlane_b32 s74, v255, 25
	v_readlane_b32 s75, v255, 26
	v_readlane_b32 s76, v255, 27
	v_readlane_b32 s77, v255, 28
	v_readlane_b32 s78, v255, 29
	v_readlane_b32 s79, v255, 30
	s_mov_b32 s80, s57
	v_readlane_b32 s93, v255, 34
	v_readlane_b32 s81, v255, 33
	v_readlane_b32 s87, v255, 32
	s_mov_b32 s70, 0xbfb8aa3b
	s_mov_b32 s71, 0x42ce8ed0
	s_cbranch_scc1 .LBB0_238
	s_barrier

.LBB0_243:
	v_and_b32_e32 v16, 15, v6
	v_and_b32_e32 v17, 48, v6
	v_lshlrev_b32_e32 v6, 2, v6
	s_and_b32 s28, s26, 3
	v_lshl_or_b32 v7, v16, 6, v17
	s_lshl_b32 s26, s20, 13
	v_and_b32_e32 v6, 32, v6
	v_lshl_add_u64 v[8:9], s[22:23], 0, v[184:185]
	v_mov_b32_e32 v129, v185
	s_nop 1
	v_bitop3_b32 v142, v7, s26, v6 bitop3:0xde
	s_lshl_b32 s26, s28, 12
	s_add_i32 s45, s38, 0x18000
	v_lshl_add_u64 v[10:11], s[22:23], 0, v[128:129]
	v_mov_b32_e32 v133, v185
	v_readlane_b32 s62, v253, 14
	v_readlane_b32 s63, v253, 15
	v_bitop3_b32 v143, v7, s26, v6 bitop3:0xde
	v_lshl_add_u64 v[6:7], v[8:9], 0, s[24:25]
	s_mov_b32 m0, s45
	s_add_i32 s46, s38, 0x1a000
	v_lshl_add_u64 v[12:13], s[62:63], 0, v[132:133]
	v_mov_b32_e32 v131, v185
	s_waitcnt vmcnt(2)
	s_barrier
	global_load_lds_dwordx4 v[6:7], off
	v_lshl_add_u64 v[6:7], v[10:11], 0, s[24:25]
	s_mov_b32 m0, s46
	s_add_i32 s47, s38, 0x8000
	s_add_i32 s48, s38, 0xa000
	s_nop 1
	v_lshl_add_u64 v[14:15], s[62:63], 0, v[130:131]
	global_load_lds_dwordx4 v[6:7], off
	v_lshl_add_u64 v[6:7], v[12:13], 0, s[24:25]
	s_mov_b32 m0, s47
	s_add_u32 s26, s22, 0x100080
	s_nop 1
	global_load_lds_dwordx4 v[6:7], off
	v_lshl_add_u64 v[6:7], v[14:15], 0, s[24:25]
	s_mov_b32 m0, s48
	s_addc_u32 s27, s23, 0
	s_add_i32 s49, s38, 0x1c000
	global_load_lds_dwordx4 v[6:7], off
	v_lshl_add_u64 v[6:7], s[26:27], 0, v[184:185]
	s_mov_b32 m0, s49
	s_add_i32 s50, s38, 0x1e000
	global_load_lds_dwordx4 v[6:7], off
	v_lshl_add_u64 v[6:7], s[26:27], 0, v[128:129]
	s_mov_b32 m0, s50
	s_nop 1
	global_load_lds_dwordx4 v[6:7], off
	s_lshl_b32 s51, s20, 2
	s_lshl_b32 s20, s28, 10
	v_readlane_b32 s4, v254, 33
	s_add_u32 s26, s4, s20
	v_readlane_b32 s4, v254, 34
	s_addc_u32 s27, s4, 0
	v_lshlrev_b32_e32 v6, 4, v17
	v_mov_b32_e32 v7, v185
	v_lshl_add_u64 v[6:7], s[26:27], 0, v[6:7]
	v_lshlrev_b32_e32 v8, 4, v16
	v_mov_b32_e32 v9, v185
	v_lshl_add_u64 v[134:135], v[6:7], 0, v[8:9]
	v_lshlrev_b32_e32 v6, 13, v4
	v_and_b32_e32 v6, 0xffffc000, v6
	v_lshl_add_u32 v3, v3, 10, v6
	v_and_b32_e32 v4, 1, v4
	v_lshl_or_b32 v3, v4, 6, v3
	v_lshl_add_u32 v138, v5, 1, v3
	v_lshlrev_b32_e32 v3, 13, v0
	v_and_b32_e32 v3, 0xffffc000, v3
	s_waitcnt vmcnt(6)
	v_lshl_add_u32 v1, v1, 10, v3
	v_and_b32_e32 v0, 1, v0
	s_nop 1
	v_lshl_or_b32 v0, v0, 6, v1
	v_readlane_b32 s58, v253, 10
	s_or_b32 s52, s51, 1
	s_or_b32 s53, s51, 2
	s_or_b32 s54, s51, 3
	v_lshl_add_u64 v[136:137], v[134:135], 0, s[94:95]
	v_mov_b32_e32 v139, v185
	v_lshl_add_u32 v140, v2, 1, v0
	v_mov_b32_e32 v141, v185
	s_mov_b32 s55, 0
	s_mov_b32 s59, s0
	s_nop 1
	s_barrier
.LBB0_244:
	s_add_i32 s55, s55, 1
	s_mov_b64 s[26:27], s[22:23]
	s_mul_i32 s22, s55, s90
	s_mov_b32 s20, s58
	s_add_i32 s58, s22, s0
	s_cmp_lt_i32 s58, 8
	s_cselect_b32 s22, s58, s20
	s_ashr_i32 s23, s22, 31
	s_nop 1
	s_lshl_b64 s[22:23], s[22:23], 10
	v_readlane_b32 s12, v253, 24
	v_readlane_b32 s13, v253, 25
	s_add_u32 s22, s12, s22
	s_addc_u32 s23, s13, s23
	s_cmp_lt_i32 s58, 8
	s_cselect_b32 s20, s23, s27
	s_cselect_b32 s60, s22, s26
	s_cmp_gt_i32 s58, 7
	s_cselect_b64 s[28:29], -1, 0
	s_add_u32 s26, s26, 0x100
	v_mov_b32_e32 v0, 0
	v_readlane_b32 s30, v255, 17
	s_nop 1
	s_addc_u32 s27, s27, 0
	s_mov_b32 s61, -2
	v_readlane_b32 s31, v255, 18
	v_mov_b32_e32 v1, v0
	v_mov_b32_e32 v2, v0
	v_mov_b32_e32 v3, v0
	v_mov_b32_e32 v4, v0
	v_mov_b32_e32 v5, v0
	v_mov_b32_e32 v6, v0
	v_mov_b32_e32 v7, v0
	v_mov_b32_e32 v8, v0
	v_mov_b32_e32 v9, v0
	v_mov_b32_e32 v10, v0
	v_mov_b32_e32 v11, v0
	v_mov_b32_e32 v12, v0
	v_mov_b32_e32 v13, v0
	v_mov_b32_e32 v14, v0
	v_mov_b32_e32 v15, v0
	v_mov_b32_e32 v16, v0
	v_mov_b32_e32 v17, v0
	v_mov_b32_e32 v18, v0
	v_mov_b32_e32 v19, v0
	v_mov_b32_e32 v20, v0
	v_mov_b32_e32 v21, v0
	v_mov_b32_e32 v22, v0
	v_mov_b32_e32 v23, v0
	v_mov_b32_e32 v24, v0
	v_mov_b32_e32 v25, v0
	v_mov_b32_e32 v26, v0
	v_mov_b32_e32 v27, v0
	v_mov_b32_e32 v28, v0
	v_mov_b32_e32 v29, v0
	v_mov_b32_e32 v30, v0
	v_mov_b32_e32 v31, v0
	v_mov_b32_e32 v32, v0
	v_mov_b32_e32 v33, v0
	v_mov_b32_e32 v34, v0
	v_mov_b32_e32 v35, v0
	v_mov_b32_e32 v36, v0
	v_mov_b32_e32 v37, v0
	v_mov_b32_e32 v38, v0
	v_mov_b32_e32 v39, v0
	v_mov_b32_e32 v40, v0
	v_mov_b32_e32 v41, v0
	v_mov_b32_e32 v42, v0
	v_mov_b32_e32 v43, v0
	v_mov_b32_e32 v44, v0
	v_mov_b32_e32 v45, v0
	v_mov_b32_e32 v46, v0
	v_mov_b32_e32 v47, v0
	v_mov_b32_e32 v48, v0
	v_mov_b32_e32 v49, v0
	v_mov_b32_e32 v50, v0
	v_mov_b32_e32 v51, v0
	v_mov_b32_e32 v52, v0
	v_mov_b32_e32 v53, v0
	v_mov_b32_e32 v54, v0
	v_mov_b32_e32 v55, v0
	v_mov_b32_e32 v56, v0
	v_mov_b32_e32 v57, v0
	v_mov_b32_e32 v58, v0
	v_mov_b32_e32 v59, v0
	v_mov_b32_e32 v60, v0
	v_mov_b32_e32 v61, v0
	v_mov_b32_e32 v62, v0
	v_mov_b32_e32 v63, v0
	v_mov_b32_e32 v64, v0
	v_mov_b32_e32 v65, v0
	v_mov_b32_e32 v66, v0
	v_mov_b32_e32 v67, v0
	v_mov_b32_e32 v68, v0
	v_mov_b32_e32 v69, v0
	v_mov_b32_e32 v70, v0
	v_mov_b32_e32 v71, v0
	v_mov_b32_e32 v72, v0
	v_mov_b32_e32 v73, v0
	v_mov_b32_e32 v74, v0
	v_mov_b32_e32 v75, v0
	v_mov_b32_e32 v76, v0
	v_mov_b32_e32 v77, v0
	v_mov_b32_e32 v78, v0
	v_mov_b32_e32 v79, v0
	v_mov_b32_e32 v80, v0
	v_mov_b32_e32 v81, v0
	v_mov_b32_e32 v82, v0
	v_mov_b32_e32 v83, v0
	v_mov_b32_e32 v84, v0
	v_mov_b32_e32 v85, v0
	v_mov_b32_e32 v86, v0
	v_mov_b32_e32 v87, v0
	v_mov_b32_e32 v88, v0
	v_mov_b32_e32 v89, v0
	v_mov_b32_e32 v90, v0
	v_mov_b32_e32 v91, v0
	v_mov_b32_e32 v92, v0
	v_mov_b32_e32 v93, v0
	v_mov_b32_e32 v94, v0
	v_mov_b32_e32 v95, v0
	v_mov_b32_e32 v96, v0
	v_mov_b32_e32 v97, v0
	v_mov_b32_e32 v98, v0
	v_mov_b32_e32 v99, v0
	v_mov_b32_e32 v100, v0
	v_mov_b32_e32 v101, v0
	v_mov_b32_e32 v102, v0
	v_mov_b32_e32 v103, v0
	v_mov_b32_e32 v104, v0
	v_mov_b32_e32 v105, v0
	v_mov_b32_e32 v106, v0
	v_mov_b32_e32 v107, v0
	v_mov_b32_e32 v108, v0
	v_mov_b32_e32 v109, v0
	v_mov_b32_e32 v110, v0
	v_mov_b32_e32 v111, v0
	v_mov_b32_e32 v112, v0
	v_mov_b32_e32 v113, v0
	v_mov_b32_e32 v114, v0
	v_mov_b32_e32 v115, v0
	v_mov_b32_e32 v116, v0
	v_mov_b32_e32 v117, v0
	v_mov_b32_e32 v118, v0
	v_mov_b32_e32 v119, v0
	v_mov_b32_e32 v120, v0
	v_mov_b32_e32 v121, v0
	v_mov_b32_e32 v122, v0
	v_mov_b32_e32 v123, v0
	v_mov_b32_e32 v124, v0
	v_mov_b32_e32 v125, v0
	v_mov_b32_e32 v126, v0
	v_mov_b32_e32 v127, v0
	v_readlane_b32 s78, v253, 14
	v_readlane_b32 s79, v253, 15
	s_nop 1
	v_readlane_b32 s65, v253, 1
	s_nop 1
	v_readlane_b32 s68, v253, 4
	v_readlane_b32 s69, v253, 5
	s_nop 1
	v_add_u32_e32 v230, 0x10000, v143

.LBB0_287:
	v_mov_b32_e32 v135, v185
	v_lshl_add_u64 v[8:9], s[28:29], 0, v[134:135]
	v_mov_b32_e32 v139, v185
	s_add_i32 s68, s58, 0x18000
	v_lshl_add_u64 v[10:11], s[28:29], 0, v[138:139]
	v_mov_b32_e32 v133, v185
	s_and_b32 s49, s20, 3
	v_lshl_add_u64 v[8:9], v[8:9], 0, s[24:25]
	s_mov_b32 m0, s68
	s_add_i32 s69, s58, 0x1a000
	v_lshl_add_u64 v[12:13], s[0:1], 0, v[132:133]
	v_mov_b32_e32 v137, v185
	s_lshl_b32 s66, s22, 6
	s_lshl_b32 s20, s22, 13
	s_lshl_b32 s23, s49, 12
	s_waitcnt vmcnt(2)
	s_barrier
	global_load_lds_dwordx4 v[8:9], off
	v_lshl_add_u64 v[8:9], v[10:11], 0, s[24:25]
	s_mov_b32 m0, s69
	s_add_i32 s70, s58, 0x8000
	s_add_i32 s71, s58, 0xa000
	v_lshl_add_u64 v[14:15], s[0:1], 0, v[136:137]
	global_load_lds_dwordx4 v[8:9], off
	v_lshl_add_u64 v[8:9], v[12:13], 0, s[24:25]
	s_mov_b32 m0, s70
	s_add_u32 s26, s28, 0x40080
	global_load_lds_dwordx4 v[8:9], off
	v_lshl_add_u64 v[8:9], v[14:15], 0, s[24:25]
	s_mov_b32 m0, s71
	s_addc_u32 s27, s29, 0
	s_add_i32 s52, s58, 0x1c000
	global_load_lds_dwordx4 v[8:9], off
	v_lshl_add_u64 v[8:9], s[26:27], 0, v[134:135]
	s_mov_b32 m0, s52
	s_add_i32 s50, s58, 0x1e000
	global_load_lds_dwordx4 v[8:9], off
	v_lshl_add_u64 v[8:9], s[26:27], 0, v[138:139]
	s_mov_b32 m0, s50
	v_bfe_u32 v7, v0, 4, 2
	global_load_lds_dwordx4 v[8:9], off
	v_and_b32_e32 v140, 15, v0
	v_lshlrev_b32_e32 v142, 4, v7
	v_lshlrev_b32_e32 v0, 2, v0
	v_lshlrev_b32_e32 v8, 3, v7
	v_lshl_or_b32 v7, v140, 6, v142
	v_and_b32_e32 v0, 32, v0
	v_bitop3_b32 v141, v7, s20, v0 bitop3:0xde
	v_bitop3_b32 v143, v7, s23, v0 bitop3:0xde
	v_lshlrev_b32_e32 v0, 14, v1
	s_lshl_b32 s67, s22, 2
	v_and_b32_e32 v0, 0xffff8000, v0
	s_add_i32 s4, s67, 8
	v_lshl_add_u32 v0, v2, 11, v0
	v_and_b32_e32 v1, 1, v1
	v_writelane_b32 v255, s4, 47
	s_add_i32 s4, s67, 9
	v_lshl_or_b32 v0, v1, 6, v0
	v_writelane_b32 v255, s4, 49
	s_add_i32 s4, s67, 10
	v_lshl_add_u32 v148, v3, 1, v0
	v_lshlrev_b32_e32 v0, 14, v4
	v_writelane_b32 v255, s4, 50
	s_add_i32 s4, s67, 11
	v_and_b32_e32 v0, 0xffff8000, v0
	s_waitcnt vmcnt(6)
	v_lshl_or_b32 v144, s49, 5, v8
	v_writelane_b32 v255, s4, 51
	s_nop 1
	v_lshl_add_u32 v0, v5, 11, v0
	v_and_b32_e32 v1, 1, v4
	v_lshlrev_b32_e32 v184, 1, v144
	v_readlane_b32 s12, v253, 24
	v_readlane_b32 s13, v253, 25
	v_lshl_or_b32 v0, v1, 6, v0
	s_or_b32 s48, s49, 0xffffffc0
	v_mov_b32_e32 v145, v185
	s_or_b32 s84, s67, 1
	s_or_b32 s85, s67, 2
	s_or_b32 s92, s67, 3
	v_or_b32_e32 v156, 0x80, v144
	s_orn2_b32 s49, s49, 59
	v_lshl_add_u64 v[146:147], s[12:13], 0, v[184:185]
	v_mov_b32_e32 v149, v185
	v_lshl_add_u32 v150, v6, 1, v0
	v_mov_b32_e32 v151, v185
	s_mov_b32 s65, 0
	s_barrier
	s_nop 1
	s_branch .LBB0_289

.LBB0_298:
	s_lshl_b32 s20, s55, 8
	s_addk_i32 s20, 0x1800
	s_cmp_eq_u32 s54, 0
	s_nop 1
	s_cselect_b32 s26, s55, s20
	v_readlane_b32 s6, v253, 18
	v_readlane_b32 s7, v253, 19
	s_cselect_b32 s20, 19, 11
	s_cselect_b32 s34, s7, s57
	s_cselect_b32 s35, s6, s56
	s_cselect_b32 s36, s56, s6
	s_cselect_b32 s37, s57, s7
	s_ashr_i32 s27, s26, 31
	s_lshl_b64 s[26:27], s[26:27], s20
	s_add_u32 s42, s35, s26
	s_addc_u32 s43, s34, s27
	s_and_b64 s[26:27], s[30:31], exec
	s_cselect_b32 s20, s43, s1
	s_cselect_b32 s34, s42, s0
	s_ashr_i32 s41, s40, 31
	s_lshl_b64 s[26:27], s[40:41], 19
	s_add_u32 s44, s36, s26
	s_addc_u32 s45, s37, s27
	s_and_b64 s[26:27], s[30:31], exec
	s_cselect_b32 s35, s45, s29
	s_cselect_b32 s36, s44, s28
	s_add_u32 s0, s0, 0x40080
	s_addc_u32 s1, s1, 0
	s_add_u32 s37, s28, 0x100
	v_mov_b32_e32 v0, 0
	s_addc_u32 s26, s29, 0
	s_mov_b32 s27, -2
	v_mov_b32_e32 v1, v0
	v_mov_b32_e32 v2, v0
	v_mov_b32_e32 v3, v0
	v_mov_b32_e32 v4, v0
	v_mov_b32_e32 v5, v0
	v_mov_b32_e32 v6, v0
	v_mov_b32_e32 v7, v0
	v_mov_b32_e32 v8, v0
	v_mov_b32_e32 v9, v0
	v_mov_b32_e32 v10, v0
	v_mov_b32_e32 v11, v0
	v_mov_b32_e32 v12, v0
	v_mov_b32_e32 v13, v0
	v_mov_b32_e32 v14, v0
	v_mov_b32_e32 v15, v0
	v_mov_b32_e32 v16, v0
	v_mov_b32_e32 v17, v0
	v_mov_b32_e32 v18, v0
	v_mov_b32_e32 v19, v0
	v_mov_b32_e32 v20, v0
	v_mov_b32_e32 v21, v0
	v_mov_b32_e32 v22, v0
	v_mov_b32_e32 v23, v0
	v_mov_b32_e32 v24, v0
	v_mov_b32_e32 v25, v0
	v_mov_b32_e32 v26, v0
	v_mov_b32_e32 v27, v0
	v_mov_b32_e32 v28, v0
	v_mov_b32_e32 v29, v0
	v_mov_b32_e32 v30, v0
	v_mov_b32_e32 v31, v0
	v_mov_b32_e32 v32, v0
	v_mov_b32_e32 v33, v0
	v_mov_b32_e32 v34, v0
	v_mov_b32_e32 v35, v0
	v_mov_b32_e32 v36, v0
	v_mov_b32_e32 v37, v0
	v_mov_b32_e32 v38, v0
	v_mov_b32_e32 v39, v0
	v_mov_b32_e32 v40, v0
	v_mov_b32_e32 v41, v0
	v_mov_b32_e32 v42, v0
	v_mov_b32_e32 v43, v0
	v_mov_b32_e32 v44, v0
	v_mov_b32_e32 v45, v0
	v_mov_b32_e32 v46, v0
	v_mov_b32_e32 v47, v0
	v_mov_b32_e32 v48, v0
	v_mov_b32_e32 v49, v0
	v_mov_b32_e32 v50, v0
	v_mov_b32_e32 v51, v0
	v_mov_b32_e32 v52, v0
	v_mov_b32_e32 v53, v0
	v_mov_b32_e32 v54, v0
	v_mov_b32_e32 v55, v0
	v_mov_b32_e32 v56, v0
	v_mov_b32_e32 v57, v0
	v_mov_b32_e32 v58, v0
	v_mov_b32_e32 v59, v0
	v_mov_b32_e32 v60, v0
	v_mov_b32_e32 v61, v0
	v_mov_b32_e32 v62, v0
	v_mov_b32_e32 v63, v0
	v_mov_b32_e32 v64, v0
	v_mov_b32_e32 v65, v0
	v_mov_b32_e32 v66, v0
	v_mov_b32_e32 v67, v0
	v_mov_b32_e32 v68, v0
	v_mov_b32_e32 v69, v0
	v_mov_b32_e32 v70, v0
	v_mov_b32_e32 v71, v0
	v_mov_b32_e32 v72, v0
	v_mov_b32_e32 v73, v0
	v_mov_b32_e32 v74, v0
	v_mov_b32_e32 v75, v0
	v_mov_b32_e32 v76, v0
	v_mov_b32_e32 v77, v0
	v_mov_b32_e32 v78, v0
	v_mov_b32_e32 v79, v0
	v_mov_b32_e32 v80, v0
	v_mov_b32_e32 v81, v0
	v_mov_b32_e32 v82, v0
	v_mov_b32_e32 v83, v0
	v_mov_b32_e32 v84, v0
	v_mov_b32_e32 v85, v0
	v_mov_b32_e32 v86, v0
	v_mov_b32_e32 v87, v0
	v_mov_b32_e32 v88, v0
	v_mov_b32_e32 v89, v0
	v_mov_b32_e32 v90, v0
	v_mov_b32_e32 v91, v0
	v_mov_b32_e32 v92, v0
	v_mov_b32_e32 v93, v0
	v_mov_b32_e32 v94, v0
	v_mov_b32_e32 v95, v0
	v_mov_b32_e32 v96, v0
	v_mov_b32_e32 v97, v0
	v_mov_b32_e32 v98, v0
	v_mov_b32_e32 v99, v0
	v_mov_b32_e32 v100, v0
	v_mov_b32_e32 v101, v0
	v_mov_b32_e32 v102, v0
	v_mov_b32_e32 v103, v0
	v_mov_b32_e32 v104, v0
	v_mov_b32_e32 v105, v0
	v_mov_b32_e32 v106, v0
	v_mov_b32_e32 v107, v0
	v_mov_b32_e32 v108, v0
	v_mov_b32_e32 v109, v0
	v_mov_b32_e32 v110, v0
	v_mov_b32_e32 v111, v0
	v_mov_b32_e32 v112, v0
	v_mov_b32_e32 v113, v0
	v_mov_b32_e32 v114, v0
	v_mov_b32_e32 v115, v0
	v_mov_b32_e32 v116, v0
	v_mov_b32_e32 v117, v0
	v_mov_b32_e32 v118, v0
	v_mov_b32_e32 v119, v0
	v_mov_b32_e32 v120, v0
	v_mov_b32_e32 v121, v0
	v_mov_b32_e32 v122, v0
	v_mov_b32_e32 v123, v0
	v_mov_b32_e32 v124, v0
	v_mov_b32_e32 v125, v0
	v_mov_b32_e32 v126, v0
	v_mov_b32_e32 v127, v0
	s_nop 1
	v_add_u32_e32 v230, 0x10000, v143
